# v43 (direct-release XCD barrier) + runtime fallback to the flat barrier when gridDim != 256
# baseline (speedup 1.0000x reference)
; DI void gbar(unsigned* ctr, unsigned& gen, unsigned G) {
;     asm volatile("s_waitcnt vmcnt(0)" ::: "memory");
;     __syncthreads();
;     gen += 1;
;     if (threadIdx.x == 0) {
;         __builtin_amdgcn_fence(__ATOMIC_RELEASE, "agent");
;         asm volatile("s_waitcnt vmcnt(0)" ::: "memory");
;         __hip_atomic_fetch_add(ctr, 1u, __ATOMIC_RELAXED, __HIP_MEMORY_SCOPE_AGENT);
;         while (__hip_atomic_load(ctr, __ATOMIC_RELAXED, __HIP_MEMORY_SCOPE_AGENT) < gen * G) __builtin_amdgcn_s_sleep(32);
;         __builtin_amdgcn_fence(__ATOMIC_ACQUIRE, "agent");
;         asm volatile("s_waitcnt vmcnt(0)" ::: "memory");
;     }
;     __syncthreads();
; }
.LBB0_1197:
	s_or_b64 exec, exec, s[18:19]
	v_cmp_gt_i32_e32 vcc, 2, v1
	v_cmp_lt_i32_e64 s[2:3], 2, v2
	s_and_b64 s[0:1], vcc, s[2:3]
	v_mov_b32_e32 v210, 0
	s_and_saveexec_b64 s[2:3], s[0:1]
	s_cbranch_execz .LBB0_1205
	s_waitcnt vmcnt(0)
	s_waitcnt lgkmcnt(0)
	v_and_b32_e32 v3, 0x3ff, v0
	v_cmp_eq_u32_e32 vcc, 0, v3
	s_waitcnt vmcnt(0)
	s_barrier
	s_and_saveexec_b64 s[4:5], vcc
	s_cbranch_execz .LBB0_1204
	s_cmp_lg_u32 s86, 0x100
	s_cbranch_scc1 .Lxb_flat_0
	s_getreg_b32 s1, hwreg(HW_REG_XCC_ID, 0, 4)
	s_lshl_b32 s1, s1, 8
	s_add_u32 s12, s42, 0x600000
	s_addc_u32 s13, s43, 0
	s_add_u32 s12, s12, s1
	s_addc_u32 s13, s13, 0
	s_add_u32 s14, s42, 0x601000
	s_addc_u32 s15, s43, 0
	s_lshr_b32 s16, s86, 3
	v_mov_b32_e32 v2, 0
	v_mov_b32_e32 v3, 1
	v_mov_b32_e32 v7, 1
	global_atomic_add v4, v2, v3, s[12:13] sc0
	v_mul_lo_u32 v8, v7, s16
	s_mov_b32 s0, 0
	s_waitcnt vmcnt(0)
	v_add_u32_e32 v4, 1, v4
	v_cmp_eq_u32_e32 vcc, v4, v8
	s_cbranch_vccz .Lxb_nl_0
	buffer_wbl2 sc1
	s_waitcnt vmcnt(0)
	global_atomic_add v4, v2, v3, s[14:15] sc0
	v_lshlrev_b32_e32 v8, 3, v7
	s_waitcnt vmcnt(0)
	v_add_u32_e32 v4, 1, v4
	v_cmp_eq_u32_e32 vcc, v4, v8
	s_cbranch_vccz .Lxb_wt_0
	global_atomic_add v2, v3, s[14:15] offset:-3968
	global_atomic_add v2, v3, s[14:15] offset:-3712
	global_atomic_add v2, v3, s[14:15] offset:-3456
	global_atomic_add v2, v3, s[14:15] offset:-3200
	global_atomic_add v2, v3, s[14:15] offset:-2944
	global_atomic_add v2, v3, s[14:15] offset:-2688
	global_atomic_add v2, v3, s[14:15] offset:-2432
	global_atomic_add v2, v3, s[14:15] offset:-2176
	global_atomic_add v2, v3, s[14:15] offset:-1920
	global_atomic_add v2, v3, s[14:15] offset:-1664
	global_atomic_add v2, v3, s[14:15] offset:-1408
	global_atomic_add v2, v3, s[14:15] offset:-1152
	global_atomic_add v2, v3, s[14:15] offset:-896
	global_atomic_add v2, v3, s[14:15] offset:-640
	global_atomic_add v2, v3, s[14:15] offset:-384
	global_atomic_add v2, v3, s[14:15] offset:-128
	buffer_inv sc1
	s_waitcnt vmcnt(0)
	s_branch .Lxb_dn_0

; DI void gbar(unsigned* ctr, unsigned& gen, unsigned G) {
;     asm volatile("s_waitcnt vmcnt(0)" ::: "memory");
;     __syncthreads();
;     gen += 1;
;     if (threadIdx.x == 0) {
;         __builtin_amdgcn_fence(__ATOMIC_RELEASE, "agent");
;         asm volatile("s_waitcnt vmcnt(0)" ::: "memory");
;         __hip_atomic_fetch_add(ctr, 1u, __ATOMIC_RELAXED, __HIP_MEMORY_SCOPE_AGENT);
;         while (__hip_atomic_load(ctr, __ATOMIC_RELAXED, __HIP_MEMORY_SCOPE_AGENT) < gen * G) __builtin_amdgcn_s_sleep(32);
;         __builtin_amdgcn_fence(__ATOMIC_ACQUIRE, "agent");
;         asm volatile("s_waitcnt vmcnt(0)" ::: "memory");
;     }
;     __syncthreads();
; }
.LBB0_1236:
	s_or_b64 exec, exec, s[22:23]
	s_cmp_lt_i32 s90, 3
	s_cselect_b64 s[0:1], -1, 0
	s_cmp_gt_i32 s91, 3
	s_cselect_b64 s[2:3], -1, 0
	s_and_b64 s[0:1], s[0:1], s[2:3]
	s_andn2_b64 vcc, exec, s[0:1]
	s_cbranch_vccnz .LBB0_1245
	s_waitcnt vmcnt(0)
	v_and_b32_e32 v1, 0x3ff, v0
	v_add_u32_e32 v210, 1, v210
	v_cmp_eq_u32_e32 vcc, 0, v1
	v_mov_b32_e32 v1, s90
	s_waitcnt lgkmcnt(0)
	v_mov_b32_e32 v5, s91
	s_waitcnt vmcnt(0)
	s_barrier
	s_and_saveexec_b64 s[2:3], vcc
	s_cbranch_execz .LBB0_1244
	s_cmp_lg_u32 s86, 0x100
	s_cbranch_scc1 .Lxb_flat_1
	s_getreg_b32 s1, hwreg(HW_REG_XCC_ID, 0, 4)
	s_lshl_b32 s1, s1, 8
	s_add_u32 s12, s42, 0x600000
	s_addc_u32 s13, s43, 0
	s_add_u32 s12, s12, s1
	s_addc_u32 s13, s13, 0
	s_add_u32 s14, s42, 0x601000
	s_addc_u32 s15, s43, 0
	s_lshr_b32 s16, s86, 3
	v_mov_b32_e32 v2, 0
	v_mov_b32_e32 v3, 1
	v_mov_b32_e32 v7, v210
	global_atomic_add v4, v2, v3, s[12:13] sc0
	v_mul_lo_u32 v8, v7, s16
	s_mov_b32 s0, 0
	s_waitcnt vmcnt(0)
	v_add_u32_e32 v4, 1, v4
	v_cmp_eq_u32_e32 vcc, v4, v8
	s_cbranch_vccz .Lxb_nl_1
	buffer_wbl2 sc1
	s_waitcnt vmcnt(0)
	global_atomic_add v4, v2, v3, s[14:15] sc0
	v_lshlrev_b32_e32 v8, 3, v7
	s_waitcnt vmcnt(0)
	v_add_u32_e32 v4, 1, v4
	v_cmp_eq_u32_e32 vcc, v4, v8
	s_cbranch_vccz .Lxb_wt_1
	global_atomic_add v2, v3, s[14:15] offset:-3968
	global_atomic_add v2, v3, s[14:15] offset:-3712
	global_atomic_add v2, v3, s[14:15] offset:-3456
	global_atomic_add v2, v3, s[14:15] offset:-3200
	global_atomic_add v2, v3, s[14:15] offset:-2944
	global_atomic_add v2, v3, s[14:15] offset:-2688
	global_atomic_add v2, v3, s[14:15] offset:-2432
	global_atomic_add v2, v3, s[14:15] offset:-2176
	global_atomic_add v2, v3, s[14:15] offset:-1920
	global_atomic_add v2, v3, s[14:15] offset:-1664
	global_atomic_add v2, v3, s[14:15] offset:-1408
	global_atomic_add v2, v3, s[14:15] offset:-1152
	global_atomic_add v2, v3, s[14:15] offset:-896
	global_atomic_add v2, v3, s[14:15] offset:-640
	global_atomic_add v2, v3, s[14:15] offset:-384
	global_atomic_add v2, v3, s[14:15] offset:-128
	buffer_inv sc1
	s_waitcnt vmcnt(0)
	s_branch .Lxb_dn_1

; DI void gbar(unsigned* ctr, unsigned& gen, unsigned G) {
;     asm volatile("s_waitcnt vmcnt(0)" ::: "memory");
;     __syncthreads();
;     gen += 1;
;     if (threadIdx.x == 0) {
;         __builtin_amdgcn_fence(__ATOMIC_RELEASE, "agent");
;         asm volatile("s_waitcnt vmcnt(0)" ::: "memory");
;         __hip_atomic_fetch_add(ctr, 1u, __ATOMIC_RELAXED, __HIP_MEMORY_SCOPE_AGENT);
;         while (__hip_atomic_load(ctr, __ATOMIC_RELAXED, __HIP_MEMORY_SCOPE_AGENT) < gen * G) __builtin_amdgcn_s_sleep(32);
;         __builtin_amdgcn_fence(__ATOMIC_ACQUIRE, "agent");
;         asm volatile("s_waitcnt vmcnt(0)" ::: "memory");
;     }
;     __syncthreads();
; }
.LBB0_1391:
	s_or_b64 exec, exec, s[72:73]
	v_cmp_gt_i32_e32 vcc, 4, v1
	v_cmp_lt_i32_e64 s[2:3], 4, v5
	s_and_b64 s[0:1], vcc, s[2:3]
	s_and_saveexec_b64 s[2:3], s[0:1]
	s_cbranch_execz .LBB0_1400
	s_waitcnt vmcnt(0)
	v_and_b32_e32 v2, 0x3ff, v0
	v_add_u32_e32 v210, 1, v210
	v_cmp_eq_u32_e32 vcc, 0, v2
	s_waitcnt vmcnt(0)
	s_barrier
	s_and_saveexec_b64 s[4:5], vcc
	s_cbranch_execz .LBB0_1399
	s_cmp_lg_u32 s86, 0x100
	s_cbranch_scc1 .Lxb_flat_2
	s_getreg_b32 s1, hwreg(HW_REG_XCC_ID, 0, 4)
	s_lshl_b32 s1, s1, 8
	s_add_u32 s12, s42, 0x600000
	s_addc_u32 s13, s43, 0
	s_add_u32 s12, s12, s1
	s_addc_u32 s13, s13, 0
	s_add_u32 s14, s42, 0x601000
	s_addc_u32 s15, s43, 0
	s_lshr_b32 s16, s86, 3
	v_mov_b32_e32 v2, 0
	v_mov_b32_e32 v3, 1
	v_mov_b32_e32 v7, v210
	global_atomic_add v4, v2, v3, s[12:13] sc0
	v_mul_lo_u32 v8, v7, s16
	s_mov_b32 s0, 0
	s_waitcnt vmcnt(0)
	v_add_u32_e32 v4, 1, v4
	v_cmp_eq_u32_e32 vcc, v4, v8
	s_cbranch_vccz .Lxb_nl_2
	buffer_wbl2 sc1
	s_waitcnt vmcnt(0)
	global_atomic_add v4, v2, v3, s[14:15] sc0
	v_lshlrev_b32_e32 v8, 3, v7
	s_waitcnt vmcnt(0)
	v_add_u32_e32 v4, 1, v4
	v_cmp_eq_u32_e32 vcc, v4, v8
	s_cbranch_vccz .Lxb_wt_2
	global_atomic_add v2, v3, s[14:15] offset:-3968
	global_atomic_add v2, v3, s[14:15] offset:-3712
	global_atomic_add v2, v3, s[14:15] offset:-3456
	global_atomic_add v2, v3, s[14:15] offset:-3200
	global_atomic_add v2, v3, s[14:15] offset:-2944
	global_atomic_add v2, v3, s[14:15] offset:-2688
	global_atomic_add v2, v3, s[14:15] offset:-2432
	global_atomic_add v2, v3, s[14:15] offset:-2176
	global_atomic_add v2, v3, s[14:15] offset:-1920
	global_atomic_add v2, v3, s[14:15] offset:-1664
	global_atomic_add v2, v3, s[14:15] offset:-1408
	global_atomic_add v2, v3, s[14:15] offset:-1152
	global_atomic_add v2, v3, s[14:15] offset:-896
	global_atomic_add v2, v3, s[14:15] offset:-640
	global_atomic_add v2, v3, s[14:15] offset:-384
	global_atomic_add v2, v3, s[14:15] offset:-128
	buffer_inv sc1
	s_waitcnt vmcnt(0)
	s_branch .Lxb_dn_2

; DI void gbar(unsigned* ctr, unsigned& gen, unsigned G) {
;     asm volatile("s_waitcnt vmcnt(0)" ::: "memory");
;     __syncthreads();
;     gen += 1;
;     if (threadIdx.x == 0) {
;         __builtin_amdgcn_fence(__ATOMIC_RELEASE, "agent");
;         asm volatile("s_waitcnt vmcnt(0)" ::: "memory");
;         __hip_atomic_fetch_add(ctr, 1u, __ATOMIC_RELAXED, __HIP_MEMORY_SCOPE_AGENT);
;         while (__hip_atomic_load(ctr, __ATOMIC_RELAXED, __HIP_MEMORY_SCOPE_AGENT) < gen * G) __builtin_amdgcn_s_sleep(32);
;         __builtin_amdgcn_fence(__ATOMIC_ACQUIRE, "agent");
;         asm volatile("s_waitcnt vmcnt(0)" ::: "memory");
;     }
;     __syncthreads();
; }
.LBB0_1445:
	s_or_b64 exec, exec, s[6:7]
	v_cmp_gt_i32_e32 vcc, 5, v1
	v_cmp_lt_i32_e64 s[2:3], 5, v5
	s_and_b64 s[0:1], vcc, s[2:3]
	s_and_saveexec_b64 s[2:3], s[0:1]
	s_cbranch_execz .LBB0_1454
	s_waitcnt vmcnt(0)
	v_and_b32_e32 v2, 0x3ff, v0
	v_add_u32_e32 v210, 1, v210
	v_cmp_eq_u32_e32 vcc, 0, v2
	s_waitcnt vmcnt(0) lgkmcnt(0)
	s_barrier
	s_and_saveexec_b64 s[4:5], vcc
	s_cbranch_execz .LBB0_1453
	s_cmp_lg_u32 s86, 0x100
	s_cbranch_scc1 .Lxb_flat_3
	s_getreg_b32 s1, hwreg(HW_REG_XCC_ID, 0, 4)
	s_lshl_b32 s1, s1, 8
	s_add_u32 s12, s42, 0x600000
	s_addc_u32 s13, s43, 0
	s_add_u32 s12, s12, s1
	s_addc_u32 s13, s13, 0
	s_add_u32 s14, s42, 0x601000
	s_addc_u32 s15, s43, 0
	s_lshr_b32 s16, s86, 3
	v_mov_b32_e32 v2, 0
	v_mov_b32_e32 v3, 1
	v_mov_b32_e32 v7, v210
	global_atomic_add v4, v2, v3, s[12:13] sc0
	v_mul_lo_u32 v8, v7, s16
	s_mov_b32 s0, 0
	s_waitcnt vmcnt(0)
	v_add_u32_e32 v4, 1, v4
	v_cmp_eq_u32_e32 vcc, v4, v8
	s_cbranch_vccz .Lxb_nl_3
	buffer_wbl2 sc1
	s_waitcnt vmcnt(0)
	global_atomic_add v4, v2, v3, s[14:15] sc0
	v_lshlrev_b32_e32 v8, 3, v7
	s_waitcnt vmcnt(0)
	v_add_u32_e32 v4, 1, v4
	v_cmp_eq_u32_e32 vcc, v4, v8
	s_cbranch_vccz .Lxb_wt_3
	global_atomic_add v2, v3, s[14:15] offset:-3968
	global_atomic_add v2, v3, s[14:15] offset:-3712
	global_atomic_add v2, v3, s[14:15] offset:-3456
	global_atomic_add v2, v3, s[14:15] offset:-3200
	global_atomic_add v2, v3, s[14:15] offset:-2944
	global_atomic_add v2, v3, s[14:15] offset:-2688
	global_atomic_add v2, v3, s[14:15] offset:-2432
	global_atomic_add v2, v3, s[14:15] offset:-2176
	global_atomic_add v2, v3, s[14:15] offset:-1920
	global_atomic_add v2, v3, s[14:15] offset:-1664
	global_atomic_add v2, v3, s[14:15] offset:-1408
	global_atomic_add v2, v3, s[14:15] offset:-1152
	global_atomic_add v2, v3, s[14:15] offset:-896
	global_atomic_add v2, v3, s[14:15] offset:-640
	global_atomic_add v2, v3, s[14:15] offset:-384
	global_atomic_add v2, v3, s[14:15] offset:-128
	buffer_inv sc1
	s_waitcnt vmcnt(0)
	s_branch .Lxb_dn_3

; DI void gbar(unsigned* ctr, unsigned& gen, unsigned G) {
;     asm volatile("s_waitcnt vmcnt(0)" ::: "memory");
;     __syncthreads();
;     gen += 1;
;     if (threadIdx.x == 0) {
;         __builtin_amdgcn_fence(__ATOMIC_RELEASE, "agent");
;         asm volatile("s_waitcnt vmcnt(0)" ::: "memory");
;         __hip_atomic_fetch_add(ctr, 1u, __ATOMIC_RELAXED, __HIP_MEMORY_SCOPE_AGENT);
;         while (__hip_atomic_load(ctr, __ATOMIC_RELAXED, __HIP_MEMORY_SCOPE_AGENT) < gen * G) __builtin_amdgcn_s_sleep(32);
;         __builtin_amdgcn_fence(__ATOMIC_ACQUIRE, "agent");
;         asm volatile("s_waitcnt vmcnt(0)" ::: "memory");
;     }
;     __syncthreads();
; }
.LBB0_1479:
	s_or_b64 exec, exec, s[4:5]
	v_cmp_gt_i32_e32 vcc, 6, v1
	v_cmp_lt_i32_e64 s[2:3], 6, v5
	s_and_b64 s[0:1], vcc, s[2:3]
	s_and_saveexec_b64 s[2:3], s[0:1]
	s_cbranch_execz .LBB0_1488
	s_waitcnt vmcnt(0)
	v_and_b32_e32 v2, 0x3ff, v0
	v_add_u32_e32 v210, 1, v210
	v_cmp_eq_u32_e32 vcc, 0, v2
	s_waitcnt vmcnt(0) lgkmcnt(0)
	s_barrier
	s_and_saveexec_b64 s[4:5], vcc
	s_cbranch_execz .LBB0_1487
	s_cmp_lg_u32 s86, 0x100
	s_cbranch_scc1 .Lxb_flat_4
	s_getreg_b32 s1, hwreg(HW_REG_XCC_ID, 0, 4)
	s_lshl_b32 s1, s1, 8
	s_add_u32 s12, s42, 0x600000
	s_addc_u32 s13, s43, 0
	s_add_u32 s12, s12, s1
	s_addc_u32 s13, s13, 0
	s_add_u32 s14, s42, 0x601000
	s_addc_u32 s15, s43, 0
	s_lshr_b32 s16, s86, 3
	v_mov_b32_e32 v2, 0
	v_mov_b32_e32 v3, 1
	v_mov_b32_e32 v7, v210
	global_atomic_add v4, v2, v3, s[12:13] sc0
	v_mul_lo_u32 v8, v7, s16
	s_mov_b32 s0, 0
	s_waitcnt vmcnt(0)
	v_add_u32_e32 v4, 1, v4
	v_cmp_eq_u32_e32 vcc, v4, v8
	s_cbranch_vccz .Lxb_nl_4
	buffer_wbl2 sc1
	s_waitcnt vmcnt(0)
	global_atomic_add v4, v2, v3, s[14:15] sc0
	v_lshlrev_b32_e32 v8, 3, v7
	s_waitcnt vmcnt(0)
	v_add_u32_e32 v4, 1, v4
	v_cmp_eq_u32_e32 vcc, v4, v8
	s_cbranch_vccz .Lxb_wt_4
	global_atomic_add v2, v3, s[14:15] offset:-3968
	global_atomic_add v2, v3, s[14:15] offset:-3712
	global_atomic_add v2, v3, s[14:15] offset:-3456
	global_atomic_add v2, v3, s[14:15] offset:-3200
	global_atomic_add v2, v3, s[14:15] offset:-2944
	global_atomic_add v2, v3, s[14:15] offset:-2688
	global_atomic_add v2, v3, s[14:15] offset:-2432
	global_atomic_add v2, v3, s[14:15] offset:-2176
	global_atomic_add v2, v3, s[14:15] offset:-1920
	global_atomic_add v2, v3, s[14:15] offset:-1664
	global_atomic_add v2, v3, s[14:15] offset:-1408
	global_atomic_add v2, v3, s[14:15] offset:-1152
	global_atomic_add v2, v3, s[14:15] offset:-896
	global_atomic_add v2, v3, s[14:15] offset:-640
	global_atomic_add v2, v3, s[14:15] offset:-384
	global_atomic_add v2, v3, s[14:15] offset:-128
	buffer_inv sc1
	s_waitcnt vmcnt(0)
	s_branch .Lxb_dn_4

; DI void gbar(unsigned* ctr, unsigned& gen, unsigned G) {
;     asm volatile("s_waitcnt vmcnt(0)" ::: "memory");
;     __syncthreads();
;     gen += 1;
;     if (threadIdx.x == 0) {
;         __builtin_amdgcn_fence(__ATOMIC_RELEASE, "agent");
;         asm volatile("s_waitcnt vmcnt(0)" ::: "memory");
;         __hip_atomic_fetch_add(ctr, 1u, __ATOMIC_RELAXED, __HIP_MEMORY_SCOPE_AGENT);
;         while (__hip_atomic_load(ctr, __ATOMIC_RELAXED, __HIP_MEMORY_SCOPE_AGENT) < gen * G) __builtin_amdgcn_s_sleep(32);
;         __builtin_amdgcn_fence(__ATOMIC_ACQUIRE, "agent");
;         asm volatile("s_waitcnt vmcnt(0)" ::: "memory");
;     }
;     __syncthreads();
; }
.LBB0_1531:
	s_or_b64 exec, exec, s[6:7]
	v_cmp_gt_i32_e32 vcc, 7, v1
	v_cmp_lt_i32_e64 s[2:3], 7, v5
	s_and_b64 s[0:1], vcc, s[2:3]
	s_and_saveexec_b64 s[2:3], s[0:1]
	s_cbranch_execz .LBB0_1540
	s_waitcnt vmcnt(0)
	v_and_b32_e32 v2, 0x3ff, v0
	v_add_u32_e32 v210, 1, v210
	v_cmp_eq_u32_e32 vcc, 0, v2
	s_waitcnt vmcnt(0) lgkmcnt(0)
	s_barrier
	s_and_saveexec_b64 s[4:5], vcc
	s_cbranch_execz .LBB0_1539
	s_cmp_lg_u32 s86, 0x100
	s_cbranch_scc1 .Lxb_flat_5
	s_getreg_b32 s1, hwreg(HW_REG_XCC_ID, 0, 4)
	s_lshl_b32 s1, s1, 8
	s_add_u32 s12, s42, 0x600000
	s_addc_u32 s13, s43, 0
	s_add_u32 s12, s12, s1
	s_addc_u32 s13, s13, 0
	s_add_u32 s14, s42, 0x601000
	s_addc_u32 s15, s43, 0
	s_lshr_b32 s16, s86, 3
	v_mov_b32_e32 v2, 0
	v_mov_b32_e32 v3, 1
	v_mov_b32_e32 v7, v210
	global_atomic_add v4, v2, v3, s[12:13] sc0
	v_mul_lo_u32 v8, v7, s16
	s_mov_b32 s0, 0
	s_waitcnt vmcnt(0)
	v_add_u32_e32 v4, 1, v4
	v_cmp_eq_u32_e32 vcc, v4, v8
	s_cbranch_vccz .Lxb_nl_5
	buffer_wbl2 sc1
	s_waitcnt vmcnt(0)
	global_atomic_add v4, v2, v3, s[14:15] sc0
	v_lshlrev_b32_e32 v8, 3, v7
	s_waitcnt vmcnt(0)
	v_add_u32_e32 v4, 1, v4
	v_cmp_eq_u32_e32 vcc, v4, v8
	s_cbranch_vccz .Lxb_wt_5
	global_atomic_add v2, v3, s[14:15] offset:-3968
	global_atomic_add v2, v3, s[14:15] offset:-3712
	global_atomic_add v2, v3, s[14:15] offset:-3456
	global_atomic_add v2, v3, s[14:15] offset:-3200
	global_atomic_add v2, v3, s[14:15] offset:-2944
	global_atomic_add v2, v3, s[14:15] offset:-2688
	global_atomic_add v2, v3, s[14:15] offset:-2432
	global_atomic_add v2, v3, s[14:15] offset:-2176
	global_atomic_add v2, v3, s[14:15] offset:-1920
	global_atomic_add v2, v3, s[14:15] offset:-1664
	global_atomic_add v2, v3, s[14:15] offset:-1408
	global_atomic_add v2, v3, s[14:15] offset:-1152
	global_atomic_add v2, v3, s[14:15] offset:-896
	global_atomic_add v2, v3, s[14:15] offset:-640
	global_atomic_add v2, v3, s[14:15] offset:-384
	global_atomic_add v2, v3, s[14:15] offset:-128
	buffer_inv sc1
	s_waitcnt vmcnt(0)
	s_branch .Lxb_dn_5

; DI void gbar(unsigned* ctr, unsigned& gen, unsigned G) {
;     asm volatile("s_waitcnt vmcnt(0)" ::: "memory");
;     __syncthreads();
;     gen += 1;
;     if (threadIdx.x == 0) {
;         __builtin_amdgcn_fence(__ATOMIC_RELEASE, "agent");
;         asm volatile("s_waitcnt vmcnt(0)" ::: "memory");
;         __hip_atomic_fetch_add(ctr, 1u, __ATOMIC_RELAXED, __HIP_MEMORY_SCOPE_AGENT);
;         while (__hip_atomic_load(ctr, __ATOMIC_RELAXED, __HIP_MEMORY_SCOPE_AGENT) < gen * G) __builtin_amdgcn_s_sleep(32);
;         __builtin_amdgcn_fence(__ATOMIC_ACQUIRE, "agent");
;         asm volatile("s_waitcnt vmcnt(0)" ::: "memory");
;     }
;     __syncthreads();
; }
.LBB0_2532:
	s_or_b64 exec, exec, s[12:13]
	v_cmp_gt_i32_e32 vcc, 8, v1
	v_cmp_lt_i32_e64 s[2:3], 8, v5
	s_and_b64 s[0:1], vcc, s[2:3]
	s_and_saveexec_b64 s[2:3], s[0:1]
	s_cbranch_execz .LBB0_2541
	s_waitcnt vmcnt(0)
	v_and_b32_e32 v2, 0x3ff, v0
	v_add_u32_e32 v210, 1, v210
	v_cmp_eq_u32_e32 vcc, 0, v2
	s_waitcnt vmcnt(0) lgkmcnt(0)
	s_barrier
	s_and_saveexec_b64 s[4:5], vcc
	s_cbranch_execz .LBB0_2540
	s_cmp_lg_u32 s86, 0x100
	s_cbranch_scc1 .Lxb_flat_6
	s_getreg_b32 s1, hwreg(HW_REG_XCC_ID, 0, 4)
	s_lshl_b32 s1, s1, 8
	s_add_u32 s12, s42, 0x600000
	s_addc_u32 s13, s43, 0
	s_add_u32 s12, s12, s1
	s_addc_u32 s13, s13, 0
	s_add_u32 s14, s42, 0x601000
	s_addc_u32 s15, s43, 0
	s_lshr_b32 s16, s86, 3
	v_mov_b32_e32 v2, 0
	v_mov_b32_e32 v3, 1
	v_mov_b32_e32 v7, v210
	global_atomic_add v4, v2, v3, s[12:13] sc0
	v_mul_lo_u32 v8, v7, s16
	s_mov_b32 s0, 0
	s_waitcnt vmcnt(0)
	v_add_u32_e32 v4, 1, v4
	v_cmp_eq_u32_e32 vcc, v4, v8
	s_cbranch_vccz .Lxb_nl_6
	buffer_wbl2 sc1
	s_waitcnt vmcnt(0)
	global_atomic_add v4, v2, v3, s[14:15] sc0
	v_lshlrev_b32_e32 v8, 3, v7
	s_waitcnt vmcnt(0)
	v_add_u32_e32 v4, 1, v4
	v_cmp_eq_u32_e32 vcc, v4, v8
	s_cbranch_vccz .Lxb_wt_6
	global_atomic_add v2, v3, s[14:15] offset:-3968
	global_atomic_add v2, v3, s[14:15] offset:-3712
	global_atomic_add v2, v3, s[14:15] offset:-3456
	global_atomic_add v2, v3, s[14:15] offset:-3200
	global_atomic_add v2, v3, s[14:15] offset:-2944
	global_atomic_add v2, v3, s[14:15] offset:-2688
	global_atomic_add v2, v3, s[14:15] offset:-2432
	global_atomic_add v2, v3, s[14:15] offset:-2176
	global_atomic_add v2, v3, s[14:15] offset:-1920
	global_atomic_add v2, v3, s[14:15] offset:-1664
	global_atomic_add v2, v3, s[14:15] offset:-1408
	global_atomic_add v2, v3, s[14:15] offset:-1152
	global_atomic_add v2, v3, s[14:15] offset:-896
	global_atomic_add v2, v3, s[14:15] offset:-640
	global_atomic_add v2, v3, s[14:15] offset:-384
	global_atomic_add v2, v3, s[14:15] offset:-128
	buffer_inv sc1
	s_waitcnt vmcnt(0)
	s_branch .Lxb_dn_6

; DI void gbar(unsigned* ctr, unsigned& gen, unsigned G) {
;     asm volatile("s_waitcnt vmcnt(0)" ::: "memory");
;     __syncthreads();
;     gen += 1;
;     if (threadIdx.x == 0) {
;         __builtin_amdgcn_fence(__ATOMIC_RELEASE, "agent");
;         asm volatile("s_waitcnt vmcnt(0)" ::: "memory");
;         __hip_atomic_fetch_add(ctr, 1u, __ATOMIC_RELAXED, __HIP_MEMORY_SCOPE_AGENT);
;         while (__hip_atomic_load(ctr, __ATOMIC_RELAXED, __HIP_MEMORY_SCOPE_AGENT) < gen * G) __builtin_amdgcn_s_sleep(32);
;         __builtin_amdgcn_fence(__ATOMIC_ACQUIRE, "agent");
;         asm volatile("s_waitcnt vmcnt(0)" ::: "memory");
;     }
;     __syncthreads();
; }
.LBB0_2545:
	s_or_b64 exec, exec, s[8:9]
	v_cmp_lt_i32_e64 s[2:3], 9, v5
	s_and_b64 s[0:1], vcc, s[2:3]
	s_and_saveexec_b64 s[2:3], s[0:1]
	s_cbranch_execz .LBB0_2554
	s_waitcnt vmcnt(0)
	v_and_b32_e32 v2, 0x3ff, v0
	v_add_u32_e32 v210, 1, v210
	v_cmp_eq_u32_e32 vcc, 0, v2
	s_waitcnt vmcnt(0)
	s_barrier
	s_and_saveexec_b64 s[4:5], vcc
	s_cbranch_execz .LBB0_2553
	s_cmp_lg_u32 s86, 0x100
	s_cbranch_scc1 .Lxb_flat_7
	s_getreg_b32 s1, hwreg(HW_REG_XCC_ID, 0, 4)
	s_lshl_b32 s1, s1, 8
	s_add_u32 s12, s42, 0x600000
	s_addc_u32 s13, s43, 0
	s_add_u32 s12, s12, s1
	s_addc_u32 s13, s13, 0
	s_add_u32 s14, s42, 0x601000
	s_addc_u32 s15, s43, 0
	s_lshr_b32 s16, s86, 3
	v_mov_b32_e32 v2, 0
	v_mov_b32_e32 v3, 1
	v_mov_b32_e32 v7, v210
	global_atomic_add v4, v2, v3, s[12:13] sc0
	v_mul_lo_u32 v8, v7, s16
	s_mov_b32 s0, 0
	s_waitcnt vmcnt(0)
	v_add_u32_e32 v4, 1, v4
	v_cmp_eq_u32_e32 vcc, v4, v8
	s_cbranch_vccz .Lxb_nl_7
	buffer_wbl2 sc1
	s_waitcnt vmcnt(0)
	global_atomic_add v4, v2, v3, s[14:15] sc0
	v_lshlrev_b32_e32 v8, 3, v7
	s_waitcnt vmcnt(0)
	v_add_u32_e32 v4, 1, v4
	v_cmp_eq_u32_e32 vcc, v4, v8
	s_cbranch_vccz .Lxb_wt_7
	global_atomic_add v2, v3, s[14:15] offset:-3968
	global_atomic_add v2, v3, s[14:15] offset:-3712
	global_atomic_add v2, v3, s[14:15] offset:-3456
	global_atomic_add v2, v3, s[14:15] offset:-3200
	global_atomic_add v2, v3, s[14:15] offset:-2944
	global_atomic_add v2, v3, s[14:15] offset:-2688
	global_atomic_add v2, v3, s[14:15] offset:-2432
	global_atomic_add v2, v3, s[14:15] offset:-2176
	global_atomic_add v2, v3, s[14:15] offset:-1920
	global_atomic_add v2, v3, s[14:15] offset:-1664
	global_atomic_add v2, v3, s[14:15] offset:-1408
	global_atomic_add v2, v3, s[14:15] offset:-1152
	global_atomic_add v2, v3, s[14:15] offset:-896
	global_atomic_add v2, v3, s[14:15] offset:-640
	global_atomic_add v2, v3, s[14:15] offset:-384
	global_atomic_add v2, v3, s[14:15] offset:-128
	buffer_inv sc1
	s_waitcnt vmcnt(0)
	s_branch .Lxb_dn_7

; DI void gbar(unsigned* ctr, unsigned& gen, unsigned G) {
;     asm volatile("s_waitcnt vmcnt(0)" ::: "memory");
;     __syncthreads();
;     gen += 1;
;     if (threadIdx.x == 0) {
;         __builtin_amdgcn_fence(__ATOMIC_RELEASE, "agent");
;         asm volatile("s_waitcnt vmcnt(0)" ::: "memory");
;         __hip_atomic_fetch_add(ctr, 1u, __ATOMIC_RELAXED, __HIP_MEMORY_SCOPE_AGENT);
;         while (__hip_atomic_load(ctr, __ATOMIC_RELAXED, __HIP_MEMORY_SCOPE_AGENT) < gen * G) __builtin_amdgcn_s_sleep(32);
;         __builtin_amdgcn_fence(__ATOMIC_ACQUIRE, "agent");
;         asm volatile("s_waitcnt vmcnt(0)" ::: "memory");
;     }
;     __syncthreads();
; }
.LBB0_3580:
	s_or_b64 exec, exec, s[2:3]
	v_cmp_gt_i32_e32 vcc, 10, v1
	v_cmp_lt_i32_e64 s[2:3], 10, v5
	s_and_b64 s[0:1], vcc, s[2:3]
	s_and_saveexec_b64 s[2:3], s[0:1]
	s_cbranch_execz .LBB0_3589
	s_waitcnt vmcnt(0)
	v_and_b32_e32 v2, 0x3ff, v0
	v_add_u32_e32 v210, 1, v210
	v_cmp_eq_u32_e32 vcc, 0, v2
	s_waitcnt vmcnt(0)
	s_barrier
	s_and_saveexec_b64 s[4:5], vcc
	s_cbranch_execz .LBB0_3588
	s_cmp_lg_u32 s86, 0x100
	s_cbranch_scc1 .Lxb_flat_8
	s_getreg_b32 s1, hwreg(HW_REG_XCC_ID, 0, 4)
	s_lshl_b32 s1, s1, 8
	s_add_u32 s12, s42, 0x600000
	s_addc_u32 s13, s43, 0
	s_add_u32 s12, s12, s1
	s_addc_u32 s13, s13, 0
	s_add_u32 s14, s42, 0x601000
	s_addc_u32 s15, s43, 0
	s_lshr_b32 s16, s86, 3
	v_mov_b32_e32 v2, 0
	v_mov_b32_e32 v3, 1
	v_mov_b32_e32 v7, v210
	global_atomic_add v4, v2, v3, s[12:13] sc0
	v_mul_lo_u32 v8, v7, s16
	s_mov_b32 s0, 0
	s_waitcnt vmcnt(0)
	v_add_u32_e32 v4, 1, v4
	v_cmp_eq_u32_e32 vcc, v4, v8
	s_cbranch_vccz .Lxb_nl_8
	buffer_wbl2 sc1
	s_waitcnt vmcnt(0)
	global_atomic_add v4, v2, v3, s[14:15] sc0
	v_lshlrev_b32_e32 v8, 3, v7
	s_waitcnt vmcnt(0)
	v_add_u32_e32 v4, 1, v4
	v_cmp_eq_u32_e32 vcc, v4, v8
	s_cbranch_vccz .Lxb_wt_8
	global_atomic_add v2, v3, s[14:15] offset:-3968
	global_atomic_add v2, v3, s[14:15] offset:-3712
	global_atomic_add v2, v3, s[14:15] offset:-3456
	global_atomic_add v2, v3, s[14:15] offset:-3200
	global_atomic_add v2, v3, s[14:15] offset:-2944
	global_atomic_add v2, v3, s[14:15] offset:-2688
	global_atomic_add v2, v3, s[14:15] offset:-2432
	global_atomic_add v2, v3, s[14:15] offset:-2176
	global_atomic_add v2, v3, s[14:15] offset:-1920
	global_atomic_add v2, v3, s[14:15] offset:-1664
	global_atomic_add v2, v3, s[14:15] offset:-1408
	global_atomic_add v2, v3, s[14:15] offset:-1152
	global_atomic_add v2, v3, s[14:15] offset:-896
	global_atomic_add v2, v3, s[14:15] offset:-640
	global_atomic_add v2, v3, s[14:15] offset:-384
	global_atomic_add v2, v3, s[14:15] offset:-128
	buffer_inv sc1
	s_waitcnt vmcnt(0)
	s_branch .Lxb_dn_8

; DI void gbar(unsigned* ctr, unsigned& gen, unsigned G) {
;     asm volatile("s_waitcnt vmcnt(0)" ::: "memory");
;     __syncthreads();
;     gen += 1;
;     if (threadIdx.x == 0) {
;         __builtin_amdgcn_fence(__ATOMIC_RELEASE, "agent");
;         asm volatile("s_waitcnt vmcnt(0)" ::: "memory");
;         __hip_atomic_fetch_add(ctr, 1u, __ATOMIC_RELAXED, __HIP_MEMORY_SCOPE_AGENT);
;         while (__hip_atomic_load(ctr, __ATOMIC_RELAXED, __HIP_MEMORY_SCOPE_AGENT) < gen * G) __builtin_amdgcn_s_sleep(32);
;         __builtin_amdgcn_fence(__ATOMIC_ACQUIRE, "agent");
;         asm volatile("s_waitcnt vmcnt(0)" ::: "memory");
;     }
;     __syncthreads();
; }
.LBB0_3644:
	s_or_b64 exec, exec, s[8:9]
	v_cmp_gt_i32_e32 vcc, 11, v1
	v_cmp_lt_i32_e64 s[2:3], 11, v5
	s_and_b64 s[0:1], vcc, s[2:3]
	s_and_saveexec_b64 s[2:3], s[0:1]
	s_cbranch_execz .LBB0_3653
	s_waitcnt vmcnt(0)
	v_and_b32_e32 v2, 0x3ff, v0
	v_add_u32_e32 v210, 1, v210
	v_cmp_eq_u32_e32 vcc, 0, v2
	s_waitcnt vmcnt(0)
	s_barrier
	s_and_saveexec_b64 s[4:5], vcc
	s_cbranch_execz .LBB0_3652
	s_cmp_lg_u32 s86, 0x100
	s_cbranch_scc1 .Lxb_flat_9
	s_getreg_b32 s1, hwreg(HW_REG_XCC_ID, 0, 4)
	s_lshl_b32 s1, s1, 8
	s_add_u32 s12, s42, 0x600000
	s_addc_u32 s13, s43, 0
	s_add_u32 s12, s12, s1
	s_addc_u32 s13, s13, 0
	s_add_u32 s14, s42, 0x601000
	s_addc_u32 s15, s43, 0
	s_lshr_b32 s16, s86, 3
	v_mov_b32_e32 v2, 0
	v_mov_b32_e32 v3, 1
	v_mov_b32_e32 v7, v210
	global_atomic_add v4, v2, v3, s[12:13] sc0
	v_mul_lo_u32 v8, v7, s16
	s_mov_b32 s0, 0
	s_waitcnt vmcnt(0)
	v_add_u32_e32 v4, 1, v4
	v_cmp_eq_u32_e32 vcc, v4, v8
	s_cbranch_vccz .Lxb_nl_9
	buffer_wbl2 sc1
	s_waitcnt vmcnt(0)
	global_atomic_add v4, v2, v3, s[14:15] sc0
	v_lshlrev_b32_e32 v8, 3, v7
	s_waitcnt vmcnt(0)
	v_add_u32_e32 v4, 1, v4
	v_cmp_eq_u32_e32 vcc, v4, v8
	s_cbranch_vccz .Lxb_wt_9
	global_atomic_add v2, v3, s[14:15] offset:-3968
	global_atomic_add v2, v3, s[14:15] offset:-3712
	global_atomic_add v2, v3, s[14:15] offset:-3456
	global_atomic_add v2, v3, s[14:15] offset:-3200
	global_atomic_add v2, v3, s[14:15] offset:-2944
	global_atomic_add v2, v3, s[14:15] offset:-2688
	global_atomic_add v2, v3, s[14:15] offset:-2432
	global_atomic_add v2, v3, s[14:15] offset:-2176
	global_atomic_add v2, v3, s[14:15] offset:-1920
	global_atomic_add v2, v3, s[14:15] offset:-1664
	global_atomic_add v2, v3, s[14:15] offset:-1408
	global_atomic_add v2, v3, s[14:15] offset:-1152
	global_atomic_add v2, v3, s[14:15] offset:-896
	global_atomic_add v2, v3, s[14:15] offset:-640
	global_atomic_add v2, v3, s[14:15] offset:-384
	global_atomic_add v2, v3, s[14:15] offset:-128
	buffer_inv sc1
	s_waitcnt vmcnt(0)
	s_branch .Lxb_dn_9

; DI void gbar(unsigned* ctr, unsigned& gen, unsigned G) {
;     asm volatile("s_waitcnt vmcnt(0)" ::: "memory");
;     __syncthreads();
;     gen += 1;
;     if (threadIdx.x == 0) {
;         __builtin_amdgcn_fence(__ATOMIC_RELEASE, "agent");
;         asm volatile("s_waitcnt vmcnt(0)" ::: "memory");
;         __hip_atomic_fetch_add(ctr, 1u, __ATOMIC_RELAXED, __HIP_MEMORY_SCOPE_AGENT);
;         while (__hip_atomic_load(ctr, __ATOMIC_RELAXED, __HIP_MEMORY_SCOPE_AGENT) < gen * G) __builtin_amdgcn_s_sleep(32);
;         __builtin_amdgcn_fence(__ATOMIC_ACQUIRE, "agent");
;         asm volatile("s_waitcnt vmcnt(0)" ::: "memory");
;     }
;     __syncthreads();
; }
.LBB0_3696:
	s_or_b64 exec, exec, s[6:7]
	v_cmp_gt_i32_e32 vcc, 12, v1
	v_cmp_lt_i32_e64 s[2:3], 12, v5
	s_and_b64 s[0:1], vcc, s[2:3]
	s_and_saveexec_b64 s[2:3], s[0:1]
	s_cbranch_execz .LBB0_3705
	s_waitcnt vmcnt(0)
	v_and_b32_e32 v2, 0x3ff, v0
	v_add_u32_e32 v210, 1, v210
	v_cmp_eq_u32_e32 vcc, 0, v2
	s_waitcnt vmcnt(0) lgkmcnt(0)
	s_barrier
	s_and_saveexec_b64 s[4:5], vcc
	s_cbranch_execz .LBB0_3704
	s_cmp_lg_u32 s86, 0x100
	s_cbranch_scc1 .Lxb_flat_10
	s_getreg_b32 s1, hwreg(HW_REG_XCC_ID, 0, 4)
	s_lshl_b32 s1, s1, 8
	s_add_u32 s12, s42, 0x600000
	s_addc_u32 s13, s43, 0
	s_add_u32 s12, s12, s1
	s_addc_u32 s13, s13, 0
	s_add_u32 s14, s42, 0x601000
	s_addc_u32 s15, s43, 0
	s_lshr_b32 s16, s86, 3
	v_mov_b32_e32 v2, 0
	v_mov_b32_e32 v3, 1
	v_mov_b32_e32 v7, v210
	global_atomic_add v4, v2, v3, s[12:13] sc0
	v_mul_lo_u32 v8, v7, s16
	s_mov_b32 s0, 0
	s_waitcnt vmcnt(0)
	v_add_u32_e32 v4, 1, v4
	v_cmp_eq_u32_e32 vcc, v4, v8
	s_cbranch_vccz .Lxb_nl_10
	buffer_wbl2 sc1
	s_waitcnt vmcnt(0)
	global_atomic_add v4, v2, v3, s[14:15] sc0
	v_lshlrev_b32_e32 v8, 3, v7
	s_waitcnt vmcnt(0)
	v_add_u32_e32 v4, 1, v4
	v_cmp_eq_u32_e32 vcc, v4, v8
	s_cbranch_vccz .Lxb_wt_10
	global_atomic_add v2, v3, s[14:15] offset:-3968
	global_atomic_add v2, v3, s[14:15] offset:-3712
	global_atomic_add v2, v3, s[14:15] offset:-3456
	global_atomic_add v2, v3, s[14:15] offset:-3200
	global_atomic_add v2, v3, s[14:15] offset:-2944
	global_atomic_add v2, v3, s[14:15] offset:-2688
	global_atomic_add v2, v3, s[14:15] offset:-2432
	global_atomic_add v2, v3, s[14:15] offset:-2176
	global_atomic_add v2, v3, s[14:15] offset:-1920
	global_atomic_add v2, v3, s[14:15] offset:-1664
	global_atomic_add v2, v3, s[14:15] offset:-1408
	global_atomic_add v2, v3, s[14:15] offset:-1152
	global_atomic_add v2, v3, s[14:15] offset:-896
	global_atomic_add v2, v3, s[14:15] offset:-640
	global_atomic_add v2, v3, s[14:15] offset:-384
	global_atomic_add v2, v3, s[14:15] offset:-128
	buffer_inv sc1
	s_waitcnt vmcnt(0)
	s_branch .Lxb_dn_10

; DI void gbar(unsigned* ctr, unsigned& gen, unsigned G) {
;     asm volatile("s_waitcnt vmcnt(0)" ::: "memory");
;     __syncthreads();
;     gen += 1;
;     if (threadIdx.x == 0) {
;         __builtin_amdgcn_fence(__ATOMIC_RELEASE, "agent");
;         asm volatile("s_waitcnt vmcnt(0)" ::: "memory");
;         __hip_atomic_fetch_add(ctr, 1u, __ATOMIC_RELAXED, __HIP_MEMORY_SCOPE_AGENT);
;         while (__hip_atomic_load(ctr, __ATOMIC_RELAXED, __HIP_MEMORY_SCOPE_AGENT) < gen * G) __builtin_amdgcn_s_sleep(32);
;         __builtin_amdgcn_fence(__ATOMIC_ACQUIRE, "agent");
;         asm volatile("s_waitcnt vmcnt(0)" ::: "memory");
;     }
;     __syncthreads();
; }
.LBB0_3730:
	s_or_b64 exec, exec, s[4:5]
	v_cmp_gt_i32_e32 vcc, 13, v1
	v_cmp_lt_i32_e64 s[2:3], 13, v5
	s_and_b64 s[0:1], vcc, s[2:3]
	s_and_saveexec_b64 s[2:3], s[0:1]
	s_cbranch_execz .LBB0_3739
	s_waitcnt vmcnt(0)
	v_and_b32_e32 v2, 0x3ff, v0
	v_add_u32_e32 v210, 1, v210
	v_cmp_eq_u32_e32 vcc, 0, v2
	s_waitcnt vmcnt(0) lgkmcnt(0)
	s_barrier
	s_and_saveexec_b64 s[4:5], vcc
	s_cbranch_execz .LBB0_3738
	s_cmp_lg_u32 s86, 0x100
	s_cbranch_scc1 .Lxb_flat_11
	s_getreg_b32 s1, hwreg(HW_REG_XCC_ID, 0, 4)
	s_lshl_b32 s1, s1, 8
	s_add_u32 s12, s42, 0x600000
	s_addc_u32 s13, s43, 0
	s_add_u32 s12, s12, s1
	s_addc_u32 s13, s13, 0
	s_add_u32 s14, s42, 0x601000
	s_addc_u32 s15, s43, 0
	s_lshr_b32 s16, s86, 3
	v_mov_b32_e32 v2, 0
	v_mov_b32_e32 v3, 1
	v_mov_b32_e32 v7, v210
	global_atomic_add v4, v2, v3, s[12:13] sc0
	v_mul_lo_u32 v8, v7, s16
	s_mov_b32 s0, 0
	s_waitcnt vmcnt(0)
	v_add_u32_e32 v4, 1, v4
	v_cmp_eq_u32_e32 vcc, v4, v8
	s_cbranch_vccz .Lxb_nl_11
	buffer_wbl2 sc1
	s_waitcnt vmcnt(0)
	global_atomic_add v4, v2, v3, s[14:15] sc0
	v_lshlrev_b32_e32 v8, 3, v7
	s_waitcnt vmcnt(0)
	v_add_u32_e32 v4, 1, v4
	v_cmp_eq_u32_e32 vcc, v4, v8
	s_cbranch_vccz .Lxb_wt_11
	global_atomic_add v2, v3, s[14:15] offset:-3968
	global_atomic_add v2, v3, s[14:15] offset:-3712
	global_atomic_add v2, v3, s[14:15] offset:-3456
	global_atomic_add v2, v3, s[14:15] offset:-3200
	global_atomic_add v2, v3, s[14:15] offset:-2944
	global_atomic_add v2, v3, s[14:15] offset:-2688
	global_atomic_add v2, v3, s[14:15] offset:-2432
	global_atomic_add v2, v3, s[14:15] offset:-2176
	global_atomic_add v2, v3, s[14:15] offset:-1920
	global_atomic_add v2, v3, s[14:15] offset:-1664
	global_atomic_add v2, v3, s[14:15] offset:-1408
	global_atomic_add v2, v3, s[14:15] offset:-1152
	global_atomic_add v2, v3, s[14:15] offset:-896
	global_atomic_add v2, v3, s[14:15] offset:-640
	global_atomic_add v2, v3, s[14:15] offset:-384
	global_atomic_add v2, v3, s[14:15] offset:-128
	buffer_inv sc1
	s_waitcnt vmcnt(0)
	s_branch .Lxb_dn_11

; DI void gbar(unsigned* ctr, unsigned& gen, unsigned G) {
;     asm volatile("s_waitcnt vmcnt(0)" ::: "memory");
;     __syncthreads();
;     gen += 1;
;     if (threadIdx.x == 0) {
;         __builtin_amdgcn_fence(__ATOMIC_RELEASE, "agent");
;         asm volatile("s_waitcnt vmcnt(0)" ::: "memory");
;         __hip_atomic_fetch_add(ctr, 1u, __ATOMIC_RELAXED, __HIP_MEMORY_SCOPE_AGENT);
;         while (__hip_atomic_load(ctr, __ATOMIC_RELAXED, __HIP_MEMORY_SCOPE_AGENT) < gen * G) __builtin_amdgcn_s_sleep(32);
;         __builtin_amdgcn_fence(__ATOMIC_ACQUIRE, "agent");
;         asm volatile("s_waitcnt vmcnt(0)" ::: "memory");
;     }
;     __syncthreads();
; }
.LBB0_3782:
	s_or_b64 exec, exec, s[6:7]
	v_cmp_gt_i32_e32 vcc, 14, v1
	v_cmp_lt_i32_e64 s[2:3], 14, v5
	s_and_b64 s[0:1], vcc, s[2:3]
	s_and_saveexec_b64 s[2:3], s[0:1]
	s_cbranch_execz .LBB0_3791
	s_waitcnt vmcnt(0)
	v_and_b32_e32 v2, 0x3ff, v0
	v_cmp_eq_u32_e32 vcc, 0, v2
	s_waitcnt vmcnt(0) lgkmcnt(0)
	s_barrier
	s_and_saveexec_b64 s[4:5], vcc
	s_cbranch_execz .LBB0_3790
	s_cmp_lg_u32 s86, 0x100
	s_cbranch_scc1 .Lxb_flat_12
	s_getreg_b32 s1, hwreg(HW_REG_XCC_ID, 0, 4)
	s_lshl_b32 s1, s1, 8
	s_add_u32 s12, s42, 0x600000
	s_addc_u32 s13, s43, 0
	s_add_u32 s12, s12, s1
	s_addc_u32 s13, s13, 0
	s_add_u32 s14, s42, 0x601000
	s_addc_u32 s15, s43, 0
	s_lshr_b32 s16, s86, 3
	v_mov_b32_e32 v2, 0
	v_mov_b32_e32 v3, 1
	v_add_u32_e32 v7, 1, v210
	global_atomic_add v4, v2, v3, s[12:13] sc0
	v_mul_lo_u32 v8, v7, s16
	s_mov_b32 s0, 0
	s_waitcnt vmcnt(0)
	v_add_u32_e32 v4, 1, v4
	v_cmp_eq_u32_e32 vcc, v4, v8
	s_cbranch_vccz .Lxb_nl_12
	buffer_wbl2 sc1
	s_waitcnt vmcnt(0)
	global_atomic_add v4, v2, v3, s[14:15] sc0
	v_lshlrev_b32_e32 v8, 3, v7
	s_waitcnt vmcnt(0)
	v_add_u32_e32 v4, 1, v4
	v_cmp_eq_u32_e32 vcc, v4, v8
	s_cbranch_vccz .Lxb_wt_12
	global_atomic_add v2, v3, s[14:15] offset:-3968
	global_atomic_add v2, v3, s[14:15] offset:-3712
	global_atomic_add v2, v3, s[14:15] offset:-3456
	global_atomic_add v2, v3, s[14:15] offset:-3200
	global_atomic_add v2, v3, s[14:15] offset:-2944
	global_atomic_add v2, v3, s[14:15] offset:-2688
	global_atomic_add v2, v3, s[14:15] offset:-2432
	global_atomic_add v2, v3, s[14:15] offset:-2176
	global_atomic_add v2, v3, s[14:15] offset:-1920
	global_atomic_add v2, v3, s[14:15] offset:-1664
	global_atomic_add v2, v3, s[14:15] offset:-1408
	global_atomic_add v2, v3, s[14:15] offset:-1152
	global_atomic_add v2, v3, s[14:15] offset:-896
	global_atomic_add v2, v3, s[14:15] offset:-640
	global_atomic_add v2, v3, s[14:15] offset:-384
	global_atomic_add v2, v3, s[14:15] offset:-128
	buffer_inv sc1
	s_waitcnt vmcnt(0)
	s_branch .Lxb_dn_12
